# att: K-row byte offsets kept in v208-239 and reused for the V-row loads (drops 16 LDS entry re-reads, 64 VALU and the serialized LDS round trips in the PV steps)
# speedup vs baseline: 1.0022x; 1.0022x over previous
.LBB0_1264:
	s_or_b64 exec, exec, s[8:9]
	v_lshrrev_b32_e32 v122, 3, v117
	v_lshl_add_u32 v119, v122, 2, s47
	s_waitcnt lgkmcnt(0)
	ds_read2_b32 v[4:5], v119 offset1:8
	ds_read2_b32 v[12:13], v119 offset0:16 offset1:24
	v_lshlrev_b32_e32 v6, 4, v120
	s_add_u32 s8, s20, s42
	v_and_b32_e32 v118, 0x70, v6
	s_waitcnt lgkmcnt(1)
	v_lshlrev_b32_e32 v4, 9, v4
	v_lshlrev_b32_e32 v5, 9, v5
	s_waitcnt lgkmcnt(0)
	v_lshlrev_b32_e32 v12, 9, v12
	v_lshlrev_b32_e32 v13, 9, v13
	s_addc_u32 s9, s21, 0
	v_and_or_b32 v208, v4, s43, v118
	v_and_or_b32 v209, v5, s43, v118
	v_and_or_b32 v210, v12, s43, v118
	v_and_or_b32 v211, v13, s43, v118
	global_load_dwordx4 v[4:7], v208, s[8:9]
	s_nop 0
	global_load_dwordx4 v[8:11], v209, s[8:9]
	ds_read2_b32 v[20:21], v119 offset0:32 offset1:40
	global_load_dwordx4 v[12:15], v210, s[8:9]
	s_nop 0
	global_load_dwordx4 v[16:19], v211, s[8:9]
	ds_read2_b32 v[28:29], v119 offset0:48 offset1:56
	s_add_u32 s18, s18, s42
	s_addc_u32 s19, s19, 0
	s_waitcnt lgkmcnt(1)
	v_lshlrev_b32_e32 v20, 9, v20
	v_lshlrev_b32_e32 v21, 9, v21
	s_waitcnt lgkmcnt(0)
	v_lshlrev_b32_e32 v28, 9, v28
	v_lshlrev_b32_e32 v29, 9, v29
	v_and_or_b32 v212, v20, s43, v118
	v_and_or_b32 v213, v21, s43, v118
	v_and_or_b32 v214, v28, s43, v118
	v_and_or_b32 v215, v29, s43, v118
	global_load_dwordx4 v[20:23], v212, s[8:9]
	s_nop 0
	global_load_dwordx4 v[24:27], v213, s[8:9]
	ds_read2_b32 v[36:37], v119 offset0:64 offset1:72
	global_load_dwordx4 v[28:31], v214, s[8:9]
	s_nop 0
	global_load_dwordx4 v[32:35], v215, s[8:9]
	ds_read2_b32 v[44:45], v119 offset0:80 offset1:88
	s_waitcnt lgkmcnt(1)
	v_lshlrev_b32_e32 v36, 9, v36
	v_lshlrev_b32_e32 v37, 9, v37
	s_waitcnt lgkmcnt(0)
	v_lshlrev_b32_e32 v44, 9, v44
	v_lshlrev_b32_e32 v45, 9, v45
	v_and_or_b32 v216, v36, s43, v118
	v_and_or_b32 v217, v37, s43, v118
	v_and_or_b32 v218, v44, s43, v118
	v_and_or_b32 v219, v45, s43, v118
	global_load_dwordx4 v[36:39], v216, s[8:9]
	s_nop 0
	global_load_dwordx4 v[40:43], v217, s[8:9]
	s_nop 0
	global_load_dwordx4 v[44:47], v218, s[8:9]
	s_nop 0
	global_load_dwordx4 v[48:51], v219, s[8:9]
	ds_read2_b32 v[52:53], v119 offset0:96 offset1:104
	ds_read2_b32 v[64:65], v119 offset0:112 offset1:120
	v_add_u32_e32 v112, s47, v112
	v_add_u32_e32 v121, s47, v118
	v_mad_u32_u24 v123, v116, s44, v112
	s_waitcnt lgkmcnt(1)
	v_lshlrev_b32_e32 v52, 9, v52
	v_lshlrev_b32_e32 v53, 9, v53
	s_waitcnt lgkmcnt(0)
	v_lshlrev_b32_e32 v64, 9, v64
	v_lshlrev_b32_e32 v65, 9, v65
	v_and_or_b32 v220, v52, s43, v118
	v_and_or_b32 v221, v53, s43, v118
	v_and_or_b32 v222, v64, s43, v118
	v_and_or_b32 v223, v65, s43, v118
	global_load_dwordx4 v[52:55], v220, s[8:9]
	s_nop 0
	global_load_dwordx4 v[60:63], v221, s[8:9]
	s_nop 0
	global_load_dwordx4 v[64:67], v222, s[8:9]
	s_nop 0
	global_load_dwordx4 v[68:71], v223, s[8:9]
	s_and_saveexec_b64 s[98:99], s[6:7]
	v_mov_b32_e32 v200, 1
	global_atomic_add v200, v113, v200, s[12:13] sc0
	s_or_b64 exec, exec, s[98:99]
	v_mad_u32_u24 v132, v122, s44, v121
	s_waitcnt vmcnt(15)
	ds_write_b128 v132, v[4:7] offset:1024
	s_waitcnt vmcnt(14)
	ds_write_b128 v132, v[8:11] offset:2304
	s_waitcnt vmcnt(13)
	ds_write_b128 v132, v[12:15] offset:3584
	s_waitcnt vmcnt(12)
	ds_write_b128 v132, v[16:19] offset:4864
	ds_read_b128 v[4:7], v123 offset:1024
	ds_read_b128 v[8:11], v123 offset:1088
	ds_read_b128 v[12:15], v123 offset:3584
	ds_read_b128 v[16:19], v123 offset:3648
	ds_read2_b32 v[72:73], v119 offset0:128 offset1:136
	ds_read2_b32 v[74:75], v119 offset0:144 offset1:152
	s_waitcnt lgkmcnt(5)
	v_mfma_f32_16x16x32_bf16 v[4:7], v[4:7], v[0:3], 0
	s_waitcnt lgkmcnt(1)
	v_lshlrev_b32_e32 v72, 9, v72
	v_mfma_f32_16x16x32_bf16 v[108:111], v[8:11], v[56:59], v[4:7]
	v_mfma_f32_16x16x32_bf16 v[12:15], v[12:15], v[0:3], 0
	s_nop 3
	v_and_or_b32 v224, v72, s43, v118
	v_lshlrev_b32_e32 v5, 9, v73
	s_waitcnt lgkmcnt(0)
	v_lshlrev_b32_e32 v72, 9, v74
	v_lshlrev_b32_e32 v73, 9, v75
	v_and_or_b32 v225, v5, s43, v118
	v_and_or_b32 v226, v72, s43, v118
	v_and_or_b32 v227, v73, s43, v118
	global_load_dwordx4 v[4:7], v224, s[8:9]
	s_nop 0
	global_load_dwordx4 v[8:11], v225, s[8:9]
	s_nop 0
	global_load_dwordx4 v[72:75], v226, s[8:9]
	s_nop 0
	global_load_dwordx4 v[76:79], v227, s[8:9]
	v_mfma_f32_16x16x32_bf16 v[104:107], v[16:19], v[56:59], v[12:15]
	s_waitcnt vmcnt(15)
	ds_write_b128 v132, v[20:23] offset:1024
	s_waitcnt vmcnt(14)
	ds_write_b128 v132, v[24:27] offset:2304
	s_waitcnt vmcnt(13)
	ds_write_b128 v132, v[28:31] offset:3584
	s_waitcnt vmcnt(12)
	ds_write_b128 v132, v[32:35] offset:4864
	ds_read_b128 v[12:15], v123 offset:1024
	ds_read_b128 v[16:19], v123 offset:1088
	ds_read_b128 v[20:23], v123 offset:3584
	ds_read_b128 v[24:27], v123 offset:3648
	ds_read2_b32 v[28:29], v119 offset0:160 offset1:168
	ds_read2_b32 v[30:31], v119 offset0:176 offset1:184
	s_waitcnt lgkmcnt(5)
	v_mfma_f32_16x16x32_bf16 v[12:15], v[12:15], v[0:3], 0
	s_waitcnt lgkmcnt(1)
	v_lshlrev_b32_e32 v28, 9, v28
	v_mfma_f32_16x16x32_bf16 v[100:103], v[16:19], v[56:59], v[12:15]
	v_mfma_f32_16x16x32_bf16 v[20:23], v[20:23], v[0:3], 0
	s_nop 3
	v_and_or_b32 v228, v28, s43, v118
	v_lshlrev_b32_e32 v13, 9, v29
	s_waitcnt lgkmcnt(0)
	v_lshlrev_b32_e32 v28, 9, v30
	v_lshlrev_b32_e32 v29, 9, v31
	v_and_or_b32 v229, v13, s43, v118
	v_and_or_b32 v230, v28, s43, v118
	v_and_or_b32 v231, v29, s43, v118
	global_load_dwordx4 v[12:15], v228, s[8:9]
	s_nop 0
	global_load_dwordx4 v[16:19], v229, s[8:9]
	s_nop 0
	global_load_dwordx4 v[28:31], v230, s[8:9]
	s_nop 0
	global_load_dwordx4 v[32:35], v231, s[8:9]
	v_mfma_f32_16x16x32_bf16 v[96:99], v[24:27], v[56:59], v[20:23]
	s_waitcnt vmcnt(15)
	ds_write_b128 v132, v[36:39] offset:1024
	s_waitcnt vmcnt(14)
	ds_write_b128 v132, v[40:43] offset:2304
	s_waitcnt vmcnt(13)
	ds_write_b128 v132, v[44:47] offset:3584
	s_waitcnt vmcnt(12)
	ds_write_b128 v132, v[48:51] offset:4864
	ds_read_b128 v[20:23], v123 offset:1024
	ds_read_b128 v[24:27], v123 offset:1088
	ds_read_b128 v[36:39], v123 offset:3584
	ds_read_b128 v[40:43], v123 offset:3648
	ds_read2_b32 v[44:45], v119 offset0:192 offset1:200
	ds_read2_b32 v[46:47], v119 offset0:208 offset1:216
	s_waitcnt lgkmcnt(5)
	v_mfma_f32_16x16x32_bf16 v[20:23], v[20:23], v[0:3], 0
	s_waitcnt lgkmcnt(1)
	v_lshlrev_b32_e32 v44, 9, v44
	v_mfma_f32_16x16x32_bf16 v[92:95], v[24:27], v[56:59], v[20:23]
	v_mfma_f32_16x16x32_bf16 v[36:39], v[36:39], v[0:3], 0
	s_nop 3
	v_and_or_b32 v232, v44, s43, v118
	v_lshlrev_b32_e32 v21, 9, v45
	s_waitcnt lgkmcnt(0)
	v_lshlrev_b32_e32 v44, 9, v46
	v_lshlrev_b32_e32 v45, 9, v47
	v_and_or_b32 v233, v21, s43, v118
	v_and_or_b32 v234, v44, s43, v118
	v_and_or_b32 v235, v45, s43, v118
	global_load_dwordx4 v[20:23], v232, s[8:9]
	s_nop 0
	global_load_dwordx4 v[24:27], v233, s[8:9]
	s_nop 0
	global_load_dwordx4 v[44:47], v234, s[8:9]
	s_nop 0
	global_load_dwordx4 v[48:51], v235, s[8:9]
	v_mfma_f32_16x16x32_bf16 v[88:91], v[40:43], v[56:59], v[36:39]
	s_waitcnt vmcnt(15)
	ds_write_b128 v132, v[52:55] offset:1024
	s_waitcnt vmcnt(14)
	ds_write_b128 v132, v[60:63] offset:2304
	s_waitcnt vmcnt(13)
	ds_write_b128 v132, v[64:67] offset:3584
	s_waitcnt vmcnt(12)
	ds_write_b128 v132, v[68:71] offset:4864
	ds_read_b128 v[36:39], v123 offset:1024
	ds_read_b128 v[40:43], v123 offset:1088
	ds_read_b128 v[52:55], v123 offset:3584
	ds_read_b128 v[60:63], v123 offset:3648
	ds_read2_b32 v[64:65], v119 offset0:224 offset1:232
	ds_read2_b32 v[66:67], v119 offset0:240 offset1:248
	s_waitcnt lgkmcnt(5)
	v_mfma_f32_16x16x32_bf16 v[36:39], v[36:39], v[0:3], 0
	s_waitcnt lgkmcnt(1)
	v_lshlrev_b32_e32 v64, 9, v64
	v_mfma_f32_16x16x32_bf16 v[84:87], v[40:43], v[56:59], v[36:39]
	v_mfma_f32_16x16x32_bf16 v[52:55], v[52:55], v[0:3], 0
	s_nop 3
	v_and_or_b32 v236, v64, s43, v118
	v_lshlrev_b32_e32 v37, 9, v65
	s_waitcnt lgkmcnt(0)
	v_lshlrev_b32_e32 v64, 9, v66
	v_and_or_b32 v237, v37, s43, v118
	v_and_or_b32 v238, v64, s43, v118
	v_lshlrev_b32_e32 v65, 9, v67
	global_load_dwordx4 v[36:39], v236, s[8:9]
	s_nop 0
	global_load_dwordx4 v[40:43], v237, s[8:9]
	v_and_or_b32 v239, v65, s43, v118
	global_load_dwordx4 v[124:127], v238, s[8:9]
	global_load_dwordx4 v[128:131], v239, s[8:9]
	v_mfma_f32_16x16x32_bf16 v[80:83], v[60:63], v[56:59], v[52:55]
	s_waitcnt vmcnt(15)
	ds_write_b128 v132, v[4:7] offset:1024
	s_waitcnt vmcnt(14)
	ds_write_b128 v132, v[8:11] offset:2304
	s_waitcnt vmcnt(13)
	ds_write_b128 v132, v[72:75] offset:3584
	s_waitcnt vmcnt(12)
	ds_write_b128 v132, v[76:79] offset:4864
	ds_read_b128 v[4:7], v123 offset:1024
	ds_read_b128 v[8:11], v123 offset:1088
	ds_read_b128 v[52:55], v123 offset:3584
	ds_read_b128 v[60:63], v123 offset:3648
	s_waitcnt lgkmcnt(3)
	v_mfma_f32_16x16x32_bf16 v[4:7], v[4:7], v[0:3], 0
	s_waitcnt lgkmcnt(1)
	v_mfma_f32_16x16x32_bf16 v[52:55], v[52:55], v[0:3], 0
	v_mfma_f32_16x16x32_bf16 v[76:79], v[8:11], v[56:59], v[4:7]
	s_waitcnt lgkmcnt(0)
	v_mfma_f32_16x16x32_bf16 v[72:75], v[60:63], v[56:59], v[52:55]
	s_waitcnt vmcnt(11)
	ds_write_b128 v132, v[12:15] offset:1024
	s_waitcnt vmcnt(10)
	ds_write_b128 v132, v[16:19] offset:2304
	s_waitcnt vmcnt(9)
	ds_write_b128 v132, v[28:31] offset:3584
	s_waitcnt vmcnt(8)
	ds_write_b128 v132, v[32:35] offset:4864
	ds_read_b128 v[4:7], v123 offset:1024
	ds_read_b128 v[8:11], v123 offset:1088
	ds_read_b128 v[12:15], v123 offset:3584
	ds_read_b128 v[16:19], v123 offset:3648
	s_waitcnt lgkmcnt(3)
	v_mfma_f32_16x16x32_bf16 v[4:7], v[4:7], v[0:3], 0
	s_waitcnt lgkmcnt(1)
	v_mfma_f32_16x16x32_bf16 v[12:15], v[12:15], v[0:3], 0
	v_mfma_f32_16x16x32_bf16 v[68:71], v[8:11], v[56:59], v[4:7]
	s_waitcnt lgkmcnt(0)
	v_mfma_f32_16x16x32_bf16 v[64:67], v[16:19], v[56:59], v[12:15]
	s_waitcnt vmcnt(7)
	ds_write_b128 v132, v[20:23] offset:1024
	s_waitcnt vmcnt(6)
	ds_write_b128 v132, v[24:27] offset:2304
	s_waitcnt vmcnt(5)
	ds_write_b128 v132, v[44:47] offset:3584
	s_waitcnt vmcnt(4)
	ds_write_b128 v132, v[48:51] offset:4864
	ds_read_b128 v[4:7], v123 offset:1024
	ds_read_b128 v[8:11], v123 offset:1088
	ds_read_b128 v[12:15], v123 offset:3584
	ds_read_b128 v[16:19], v123 offset:3648
	s_waitcnt lgkmcnt(3)
	v_mfma_f32_16x16x32_bf16 v[4:7], v[4:7], v[0:3], 0
	s_waitcnt lgkmcnt(1)
	v_mfma_f32_16x16x32_bf16 v[12:15], v[12:15], v[0:3], 0
	v_mfma_f32_16x16x32_bf16 v[60:63], v[8:11], v[56:59], v[4:7]
	s_waitcnt lgkmcnt(0)
	v_mfma_f32_16x16x32_bf16 v[52:55], v[16:19], v[56:59], v[12:15]
	s_waitcnt vmcnt(3)
	ds_write_b128 v132, v[36:39] offset:1024
	s_waitcnt vmcnt(2)
	ds_write_b128 v132, v[40:43] offset:2304
	s_waitcnt vmcnt(1)
	ds_write_b128 v132, v[124:127] offset:3584
	s_waitcnt vmcnt(0)
	ds_write_b128 v132, v[128:131] offset:4864
	v_readfirstlane_b32 s100, v200
	s_ashr_i32 s101, s100, 31
	s_lshl_b64 s[100:101], s[100:101], 10
	s_add_u32 s100, s39, s100
	s_addc_u32 s101, s40, s101
	v_lshlrev_b32_e32 v204, 4, v117
	global_load_dwordx4 v[204:207], v204, s[100:101]
	ds_read_b128 v[4:7], v123 offset:1024
	ds_read_b128 v[8:11], v123 offset:1088
	ds_read_b128 v[12:15], v123 offset:3584
	ds_read_b128 v[124:127], v123 offset:3648
	s_waitcnt lgkmcnt(3)
	v_mfma_f32_16x16x32_bf16 v[4:7], v[4:7], v[0:3], 0
	s_waitcnt lgkmcnt(1)
	v_mfma_f32_16x16x32_bf16 v[128:131], v[12:15], v[0:3], 0
	s_waitcnt lgkmcnt(0)
	global_load_dwordx4 v[32:35], v208, s[18:19]
	global_load_dwordx4 v[36:39], v209, s[18:19]
	global_load_dwordx4 v[40:43], v210, s[18:19]
	global_load_dwordx4 v[44:47], v211, s[18:19]
	global_load_dwordx4 v[16:19], v212, s[18:19]
	global_load_dwordx4 v[20:23], v213, s[18:19]
	v_mfma_f32_16x16x32_bf16 v[48:51], v[8:11], v[56:59], v[4:7]
	global_load_dwordx4 v[24:27], v214, s[18:19]
	global_load_dwordx4 v[28:31], v215, s[18:19]
	v_mfma_f32_16x16x32_bf16 v[56:59], v[124:127], v[56:59], v[128:131]
	global_load_dwordx4 v[0:3], v216, s[18:19]
	s_nop 0
	global_load_dwordx4 v[4:7], v217, s[18:19]
	s_nop 0
	global_load_dwordx4 v[8:11], v218, s[18:19]
	s_nop 0
	global_load_dwordx4 v[12:15], v219, s[18:19]
	v_and_b32_e32 v123, 12, v116
	v_add_u32_e32 v123, v112, v123
	v_and_b32_e32 v112, 3, v120
	v_lshl_add_u32 v112, v112, 2, s41
	ds_read_b32 v136, v123
	ds_read_b32 v137, v123 offset:64
	ds_read_b32 v138, v123 offset:128
	ds_read_b32 v139, v123 offset:192
	ds_read_b32 v140, v123 offset:256
	ds_read_b32 v141, v123 offset:320
	ds_read_b32 v142, v123 offset:384
	ds_read_b32 v143, v123 offset:448
	ds_read_b32 v144, v123 offset:512
	ds_read_b32 v145, v123 offset:576
	ds_read_b32 v146, v123 offset:640
	ds_read_b32 v147, v123 offset:704
	ds_read_b32 v148, v123 offset:768
	ds_read_b32 v149, v123 offset:832
	ds_read_b32 v150, v123 offset:896
	ds_read_b32 v151, v123 offset:960
	s_movk_i32 s8, 0x7c0
	v_mov_b32_e32 v168, 0xf149f2ca
	v_mov_b32_dpp v108, v109 row_shr:4 row_mask:0xf bank_mask:0x2
	v_mov_b32_dpp v104, v105 row_shr:4 row_mask:0xf bank_mask:0x2
	v_mov_b32_dpp v100, v101 row_shr:4 row_mask:0xf bank_mask:0x2
	v_mov_b32_dpp v96, v97 row_shr:4 row_mask:0xf bank_mask:0x2
	v_mov_b32_dpp v92, v93 row_shr:4 row_mask:0xf bank_mask:0x2
	v_mov_b32_dpp v88, v89 row_shr:4 row_mask:0xf bank_mask:0x2
	v_mov_b32_dpp v84, v85 row_shr:4 row_mask:0xf bank_mask:0x2
	v_mov_b32_dpp v80, v81 row_shr:4 row_mask:0xf bank_mask:0x2
	v_mov_b32_dpp v76, v77 row_shr:4 row_mask:0xf bank_mask:0x2
	v_mov_b32_dpp v72, v73 row_shr:4 row_mask:0xf bank_mask:0x2
	v_mov_b32_dpp v68, v69 row_shr:4 row_mask:0xf bank_mask:0x2
	v_mov_b32_dpp v64, v65 row_shr:4 row_mask:0xf bank_mask:0x2
	v_mov_b32_dpp v60, v61 row_shr:4 row_mask:0xf bank_mask:0x2
	v_mov_b32_dpp v52, v53 row_shr:4 row_mask:0xf bank_mask:0x2
	v_mov_b32_dpp v48, v49 row_shr:4 row_mask:0xf bank_mask:0x2
	v_mov_b32_dpp v56, v57 row_shr:4 row_mask:0xf bank_mask:0x2
	v_mov_b32_dpp v108, v110 row_shr:8 row_mask:0xf bank_mask:0x4
	v_mov_b32_dpp v104, v106 row_shr:8 row_mask:0xf bank_mask:0x4
	v_mov_b32_dpp v100, v102 row_shr:8 row_mask:0xf bank_mask:0x4
	v_mov_b32_dpp v96, v98 row_shr:8 row_mask:0xf bank_mask:0x4
	v_mov_b32_dpp v92, v94 row_shr:8 row_mask:0xf bank_mask:0x4
	v_mov_b32_dpp v88, v90 row_shr:8 row_mask:0xf bank_mask:0x4
	v_mov_b32_dpp v84, v86 row_shr:8 row_mask:0xf bank_mask:0x4
	v_mov_b32_dpp v80, v82 row_shr:8 row_mask:0xf bank_mask:0x4
	v_mov_b32_dpp v76, v78 row_shr:8 row_mask:0xf bank_mask:0x4
	v_mov_b32_dpp v72, v74 row_shr:8 row_mask:0xf bank_mask:0x4
	v_mov_b32_dpp v68, v70 row_shr:8 row_mask:0xf bank_mask:0x4
	v_mov_b32_dpp v64, v66 row_shr:8 row_mask:0xf bank_mask:0x4
	v_mov_b32_dpp v60, v62 row_shr:8 row_mask:0xf bank_mask:0x4
	v_mov_b32_dpp v52, v54 row_shr:8 row_mask:0xf bank_mask:0x4
	v_mov_b32_dpp v48, v50 row_shr:8 row_mask:0xf bank_mask:0x4
	v_mov_b32_dpp v56, v58 row_shr:8 row_mask:0xf bank_mask:0x4
	v_mov_b32_dpp v108, v111 row_shr:12 row_mask:0xf bank_mask:0x8
	v_mov_b32_dpp v104, v107 row_shr:12 row_mask:0xf bank_mask:0x8
	v_mov_b32_dpp v100, v103 row_shr:12 row_mask:0xf bank_mask:0x8
	v_mov_b32_dpp v96, v99 row_shr:12 row_mask:0xf bank_mask:0x8
	v_mov_b32_dpp v92, v95 row_shr:12 row_mask:0xf bank_mask:0x8
	v_mov_b32_dpp v88, v91 row_shr:12 row_mask:0xf bank_mask:0x8
	v_mov_b32_dpp v84, v87 row_shr:12 row_mask:0xf bank_mask:0x8
	v_mov_b32_dpp v80, v83 row_shr:12 row_mask:0xf bank_mask:0x8
	v_mov_b32_dpp v76, v79 row_shr:12 row_mask:0xf bank_mask:0x8
	v_mov_b32_dpp v72, v75 row_shr:12 row_mask:0xf bank_mask:0x8
	v_mov_b32_dpp v68, v71 row_shr:12 row_mask:0xf bank_mask:0x8
	v_mov_b32_dpp v64, v67 row_shr:12 row_mask:0xf bank_mask:0x8
	v_mov_b32_dpp v60, v63 row_shr:12 row_mask:0xf bank_mask:0x8
	v_mov_b32_dpp v52, v55 row_shr:12 row_mask:0xf bank_mask:0x8
	v_mov_b32_dpp v48, v51 row_shr:12 row_mask:0xf bank_mask:0x8
	v_mov_b32_dpp v56, v59 row_shr:12 row_mask:0xf bank_mask:0x8
	s_waitcnt lgkmcnt(15)
	v_lshrrev_b32_e32 v152, 10, v136
	v_and_or_b32 v152, v152, s8, v112
	s_waitcnt lgkmcnt(14)
	v_lshrrev_b32_e32 v153, 10, v137
	v_and_or_b32 v153, v153, s8, v112
	s_waitcnt lgkmcnt(13)
	v_lshrrev_b32_e32 v154, 10, v138
	v_and_or_b32 v154, v154, s8, v112
	s_waitcnt lgkmcnt(12)
	v_lshrrev_b32_e32 v155, 10, v139
	v_and_or_b32 v155, v155, s8, v112
	s_waitcnt lgkmcnt(11)
	v_lshrrev_b32_e32 v156, 10, v140
	v_and_or_b32 v156, v156, s8, v112
	s_waitcnt lgkmcnt(10)
	v_lshrrev_b32_e32 v157, 10, v141
	v_and_or_b32 v157, v157, s8, v112
	s_waitcnt lgkmcnt(9)
	v_lshrrev_b32_e32 v158, 10, v142
	v_and_or_b32 v158, v158, s8, v112
	s_waitcnt lgkmcnt(8)
	v_lshrrev_b32_e32 v159, 10, v143
	v_and_or_b32 v159, v159, s8, v112
	s_waitcnt lgkmcnt(7)
	v_lshrrev_b32_e32 v160, 10, v144
	v_and_or_b32 v160, v160, s8, v112
	s_waitcnt lgkmcnt(6)
	v_lshrrev_b32_e32 v161, 10, v145
	v_and_or_b32 v161, v161, s8, v112
	s_waitcnt lgkmcnt(5)
	v_lshrrev_b32_e32 v162, 10, v146
	v_and_or_b32 v162, v162, s8, v112
	s_waitcnt lgkmcnt(4)
	v_lshrrev_b32_e32 v163, 10, v147
	v_and_or_b32 v163, v163, s8, v112
	s_waitcnt lgkmcnt(3)
	v_lshrrev_b32_e32 v164, 10, v148
	v_and_or_b32 v164, v164, s8, v112
	s_waitcnt lgkmcnt(2)
	v_lshrrev_b32_e32 v165, 10, v149
	v_and_or_b32 v165, v165, s8, v112
	s_waitcnt lgkmcnt(1)
	v_lshrrev_b32_e32 v166, 10, v150
	v_and_or_b32 v166, v166, s8, v112
	s_waitcnt lgkmcnt(0)
	v_lshrrev_b32_e32 v167, 10, v151
	v_and_or_b32 v167, v167, s8, v112
	ds_read_b32 v152, v152
	ds_read_b32 v153, v153
	ds_read_b32 v154, v154
	ds_read_b32 v155, v155
	ds_read_b32 v156, v156
	ds_read_b32 v157, v157
	ds_read_b32 v158, v158
	ds_read_b32 v159, v159
	ds_read_b32 v160, v160
	ds_read_b32 v161, v161
	ds_read_b32 v162, v162
	ds_read_b32 v163, v163
	ds_read_b32 v164, v164
	ds_read_b32 v165, v165
	ds_read_b32 v166, v166
	ds_read_b32 v167, v167
	s_waitcnt lgkmcnt(15)
	v_fmac_f32_e32 v152, 0x3e000000, v108
	v_cmp_lt_u32_e64 s[20:21], s45, v136
	s_waitcnt lgkmcnt(14)
	v_fmac_f32_e32 v153, 0x3e000000, v104
	v_cmp_lt_u32_e64 s[8:9], s45, v137
	v_cndmask_b32_e64 v110, v168, v152, s[20:21]
	s_waitcnt lgkmcnt(13)
	v_fmac_f32_e32 v154, 0x3e000000, v100
	v_cmp_lt_u32_e64 s[20:21], s45, v138
	v_cndmask_b32_e64 v109, v168, v153, s[8:9]
	s_waitcnt lgkmcnt(12)
	v_fmac_f32_e32 v155, 0x3e000000, v96
	v_cmp_lt_u32_e64 s[8:9], s45, v139
	v_cndmask_b32_e64 v102, v168, v154, s[20:21]
	s_waitcnt lgkmcnt(11)
	v_fmac_f32_e32 v156, 0x3e000000, v92
	v_cmp_lt_u32_e64 s[20:21], s45, v140
	v_cndmask_b32_e64 v101, v168, v155, s[8:9]
	s_waitcnt lgkmcnt(10)
	v_fmac_f32_e32 v157, 0x3e000000, v88
	v_cmp_lt_u32_e64 s[8:9], s45, v141
	v_cndmask_b32_e64 v94, v168, v156, s[20:21]
	s_waitcnt lgkmcnt(9)
	v_fmac_f32_e32 v158, 0x3e000000, v84
	v_cmp_lt_u32_e64 s[20:21], s45, v142
	v_cndmask_b32_e64 v93, v168, v157, s[8:9]
	s_waitcnt lgkmcnt(8)
	v_fmac_f32_e32 v159, 0x3e000000, v80
	v_cmp_lt_u32_e64 s[8:9], s45, v143
	v_cndmask_b32_e64 v86, v168, v158, s[20:21]
	s_waitcnt lgkmcnt(7)
	v_fmac_f32_e32 v160, 0x3e000000, v76
	v_cmp_lt_u32_e64 s[20:21], s45, v144
	v_cndmask_b32_e64 v85, v168, v159, s[8:9]
	s_waitcnt lgkmcnt(6)
	v_fmac_f32_e32 v161, 0x3e000000, v72
	v_cmp_lt_u32_e64 s[8:9], s45, v145
	v_cndmask_b32_e64 v78, v168, v160, s[20:21]
	s_waitcnt lgkmcnt(5)
	v_fmac_f32_e32 v162, 0x3e000000, v68
	v_cmp_lt_u32_e64 s[20:21], s45, v146
	v_cndmask_b32_e64 v77, v168, v161, s[8:9]
	s_waitcnt lgkmcnt(4)
	v_fmac_f32_e32 v163, 0x3e000000, v64
	v_cmp_lt_u32_e64 s[8:9], s45, v147
	v_cndmask_b32_e64 v70, v168, v162, s[20:21]
	s_waitcnt lgkmcnt(3)
	v_fmac_f32_e32 v164, 0x3e000000, v60
	v_cmp_lt_u32_e64 s[20:21], s45, v148
	v_cndmask_b32_e64 v69, v168, v163, s[8:9]
	s_waitcnt lgkmcnt(2)
	v_fmac_f32_e32 v165, 0x3e000000, v52
	v_cmp_lt_u32_e64 s[8:9], s45, v149
	v_cndmask_b32_e64 v62, v168, v164, s[20:21]
	s_waitcnt lgkmcnt(1)
	v_fmac_f32_e32 v166, 0x3e000000, v48
	v_cmp_lt_u32_e64 s[20:21], s45, v150
	v_cndmask_b32_e64 v61, v168, v165, s[8:9]
	s_waitcnt lgkmcnt(0)
	v_fmac_f32_e32 v167, 0x3e000000, v56
	v_cmp_lt_u32_e64 s[8:9], s45, v151
	v_cndmask_b32_e64 v50, v168, v166, s[20:21]
	s_nop 1
	v_cndmask_b32_e64 v49, v168, v167, s[8:9]
	v_max3_f32 v48, v110, s46, v109
	v_max3_f32 v48, v48, v102, v101
	v_max3_f32 v48, v48, v94, v93
	v_max3_f32 v48, v48, v86, v85
	v_max3_f32 v48, v48, v78, v77
	v_max3_f32 v48, v48, v70, v69
	v_max3_f32 v48, v48, v62, v61
	v_max3_f32 v48, v48, v50, v49
	v_mov_b32_e32 v51, v113
	v_mov_b32_e32 v68, v113
	v_bfe_u32 v98, v120, 4, 2
	v_mov_b32_dpp v51, v48 row_ror:4 row_mask:0xf bank_mask:0xf
	v_max_f32_e32 v51, v51, v51
	v_max_f32_e32 v48, v48, v51
	v_mov_b32_e32 v51, v113
	v_lshrrev_b32_e32 v100, 2, v116
	v_lshl_or_b32 v98, v98, 2, v100
	v_mov_b32_dpp v51, v48 row_ror:8 row_mask:0xf bank_mask:0xf
	v_max_f32_e32 v51, v51, v51
	v_max_f32_e32 v48, v48, v51
	v_mov_b32_e32 v51, v48
	s_nop 1
	v_permlane16_swap_b32_e32 v48, v51
	v_max_f32_e32 v51, v51, v51
	v_max_f32_e32 v48, v48, v48
	v_max_f32_e32 v48, v48, v51
	v_mov_b32_e32 v51, v48
	s_nop 1
	v_permlane32_swap_b32_e32 v48, v51
	v_max_f32_e32 v51, v51, v51
	v_max_f32_e32 v48, v48, v48
	v_max_f32_e32 v48, v48, v51
	v_sub_f32_e32 v51, v110, v48
	v_mul_f32_e32 v51, 0x3fb8aa3b, v51
	v_sub_f32_e32 v52, v109, v48
	v_exp_f32_e32 v51, v51
	v_mul_f32_e32 v52, 0x3fb8aa3b, v52
	v_sub_f32_e32 v53, v102, v48
	v_exp_f32_e32 v52, v52
	v_mul_f32_e32 v53, 0x3fb8aa3b, v53
	v_sub_f32_e32 v54, v101, v48
	v_exp_f32_e32 v53, v53
	v_mul_f32_e32 v54, 0x3fb8aa3b, v54
	v_sub_f32_e32 v56, v94, v48
	v_exp_f32_e32 v54, v54
	v_mul_f32_e32 v56, 0x3fb8aa3b, v56
	v_sub_f32_e32 v57, v93, v48
	v_add_f32_e32 v55, 0, v51
	v_exp_f32_e32 v56, v56
	v_mul_f32_e32 v57, 0x3fb8aa3b, v57
	v_sub_f32_e32 v58, v86, v48
	v_add_f32_e32 v55, v52, v55
	v_exp_f32_e32 v57, v57
	v_mul_f32_e32 v58, 0x3fb8aa3b, v58
	v_sub_f32_e32 v59, v85, v48
	v_add_f32_e32 v55, v53, v55
	v_exp_f32_e32 v58, v58
	v_mul_f32_e32 v59, 0x3fb8aa3b, v59
	v_sub_f32_e32 v60, v78, v48
	v_add_f32_e32 v55, v54, v55
	v_exp_f32_e32 v59, v59
	v_mul_f32_e32 v60, 0x3fb8aa3b, v60
	v_sub_f32_e32 v63, v77, v48
	v_sub_f32_e32 v64, v70, v48
	v_add_f32_e32 v55, v56, v55
	v_exp_f32_e32 v60, v60
	v_mul_f32_e32 v63, 0x3fb8aa3b, v63
	v_mul_f32_e32 v64, 0x3fb8aa3b, v64
	v_add_f32_e32 v55, v57, v55
	v_exp_f32_e32 v63, v63
	v_exp_f32_e32 v101, v64
	v_sub_f32_e32 v64, v69, v48
	v_add_f32_e32 v55, v58, v55
	v_mul_f32_e32 v64, 0x3fb8aa3b, v64
	v_sub_f32_e32 v62, v62, v48
	v_add_f32_e32 v55, v59, v55
	v_exp_f32_e32 v102, v64
	v_mul_f32_e32 v62, 0x3fb8aa3b, v62
	v_sub_f32_e32 v61, v61, v48
	v_add_f32_e32 v55, v60, v55
	v_exp_f32_e32 v103, v62
	v_mul_f32_e32 v61, 0x3fb8aa3b, v61
	v_sub_f32_e32 v50, v50, v48
	v_add_f32_e32 v55, v63, v55
	v_exp_f32_e32 v104, v61
	v_mul_f32_e32 v50, 0x3fb8aa3b, v50
	v_sub_f32_e32 v48, v49, v48
	v_add_f32_e32 v55, v101, v55
	v_exp_f32_e32 v105, v50
	v_mul_f32_e32 v48, 0x3fb8aa3b, v48
	v_add_f32_e32 v55, v102, v55
	v_exp_f32_e32 v106, v48
	v_add_f32_e32 v48, v103, v55
	v_add_f32_e32 v48, v104, v48
	v_add_f32_e32 v48, v105, v48
	v_add_f32_e32 v48, v106, v48
	v_mov_b32_e32 v50, v113
	v_mov_b32_e32 v55, v113
	v_add_f32_dpp v48, v48, v48 row_ror:4 row_mask:0xf bank_mask:0xf bound_ctrl:1
	v_mov_b32_e32 v61, v113
	v_mov_b32_dpp v50, v51 row_shl:8 row_mask:0xf bank_mask:0x1 bound_ctrl:1
	v_add_f32_dpp v48, v48, v48 row_ror:8 row_mask:0xf bank_mask:0xf bound_ctrl:1
	v_mov_b32_e32 v49, v48
	s_nop 1
	v_permlane16_swap_b32_e32 v48, v49
	v_add_f32_e32 v96, v48, v49
	v_mov_b32_e32 v49, v113
	v_cndmask_b32_e32 v48, 0, v51, vcc
	v_mov_b32_dpp v55, v51 row_shl:12 row_mask:0xf bank_mask:0x1 bound_ctrl:1
	v_mov_b32_dpp v49, v51 row_shl:4 row_mask:0xf bank_mask:0x1 bound_ctrl:1
	v_cndmask_b32_e32 v51, 0, v52, vcc
	v_mov_b32_dpp v61, v52 row_shl:4 row_mask:0xf bank_mask:0x1 bound_ctrl:1
	v_mov_b32_e32 v62, v113
	v_mov_b32_e32 v64, v113
	v_cvt_pk_bf16_f32 v76, v48, v49
	v_cvt_pk_bf16_f32 v77, v50, v55
	v_cvt_pk_bf16_f32 v78, v51, v61
	v_mov_b32_e32 v49, v113
	v_mov_b32_e32 v50, v113
	v_mov_b32_e32 v51, v113
	v_mov_b32_dpp v62, v52 row_shl:8 row_mask:0xf bank_mask:0x1 bound_ctrl:1
	v_mov_b32_dpp v64, v52 row_shl:12 row_mask:0xf bank_mask:0x1 bound_ctrl:1
	v_cndmask_b32_e32 v48, 0, v53, vcc
	v_mov_b32_dpp v49, v53 row_shl:4 row_mask:0xf bank_mask:0x1 bound_ctrl:1
	v_mov_b32_dpp v50, v53 row_shl:8 row_mask:0xf bank_mask:0x1 bound_ctrl:1
	v_mov_b32_dpp v51, v53 row_shl:12 row_mask:0xf bank_mask:0x1 bound_ctrl:1
	v_cvt_pk_bf16_f32 v79, v62, v64
	v_mov_b32_e32 v53, v113
	v_cvt_pk_bf16_f32 v64, v48, v49
	v_cvt_pk_bf16_f32 v65, v50, v51
	v_mov_b32_e32 v49, v113
	v_mov_b32_e32 v50, v113
	v_mov_b32_e32 v51, v113
	v_cndmask_b32_e32 v52, 0, v54, vcc
	v_mov_b32_dpp v53, v54 row_shl:4 row_mask:0xf bank_mask:0x1 bound_ctrl:1
	v_cndmask_b32_e32 v48, 0, v56, vcc
	v_mov_b32_dpp v49, v56 row_shl:4 row_mask:0xf bank_mask:0x1 bound_ctrl:1
	v_mov_b32_dpp v50, v56 row_shl:8 row_mask:0xf bank_mask:0x1 bound_ctrl:1
	v_mov_b32_dpp v51, v56 row_shl:12 row_mask:0xf bank_mask:0x1 bound_ctrl:1
	v_cvt_pk_bf16_f32 v66, v52, v53
	v_cvt_pk_bf16_f32 v52, v48, v49
	v_cvt_pk_bf16_f32 v53, v50, v51
	v_mov_b32_e32 v51, v113
	v_cndmask_b32_e32 v50, 0, v58, vcc
	v_mov_b32_dpp v51, v58 row_shl:4 row_mask:0xf bank_mask:0x1 bound_ctrl:1
	v_cvt_pk_bf16_f32 v72, v50, v51
	global_load_dwordx4 v[80:83], v220, s[18:19]
	global_load_dwordx4 v[84:87], v221, s[18:19]
	global_load_dwordx4 v[88:91], v222, s[18:19]
	global_load_dwordx4 v[92:95], v223, s[18:19]
	v_mov_b32_e32 v55, v113
	v_mov_b32_e32 v61, v113
	v_mov_b32_e32 v56, v113
	v_mov_b32_dpp v55, v54 row_shl:8 row_mask:0xf bank_mask:0x1 bound_ctrl:1
	v_mov_b32_dpp v61, v54 row_shl:12 row_mask:0xf bank_mask:0x1 bound_ctrl:1
	v_cvt_pk_bf16_f32 v67, v55, v61
	v_mov_b32_e32 v55, v113
	v_mov_b32_e32 v61, v113
	v_cndmask_b32_e32 v54, 0, v57, vcc
	v_mov_b32_dpp v55, v57 row_shl:4 row_mask:0xf bank_mask:0x1 bound_ctrl:1
	v_mov_b32_dpp v56, v57 row_shl:8 row_mask:0xf bank_mask:0x1 bound_ctrl:1
	v_mov_b32_dpp v61, v57 row_shl:12 row_mask:0xf bank_mask:0x1 bound_ctrl:1
	v_cvt_pk_bf16_f32 v54, v54, v55
	v_cvt_pk_bf16_f32 v55, v56, v61
	v_mov_b32_e32 v56, v113
	v_mov_b32_e32 v57, v113
	v_mov_b32_e32 v61, v113
	v_mov_b32_dpp v56, v58 row_shl:8 row_mask:0xf bank_mask:0x1 bound_ctrl:1
	v_mov_b32_dpp v57, v58 row_shl:12 row_mask:0xf bank_mask:0x1 bound_ctrl:1
	v_cndmask_b32_e32 v58, 0, v59, vcc
	v_mov_b32_dpp v61, v59 row_shl:4 row_mask:0xf bank_mask:0x1 bound_ctrl:1
	v_mov_b32_e32 v62, v113
	v_mov_b32_dpp v68, v59 row_shl:12 row_mask:0xf bank_mask:0x1 bound_ctrl:1
	v_cvt_pk_bf16_f32 v74, v58, v61
	v_mov_b32_dpp v62, v59 row_shl:8 row_mask:0xf bank_mask:0x1 bound_ctrl:1
	v_mov_b32_e32 v49, v113
	v_mov_b32_e32 v50, v113
	v_mov_b32_e32 v51, v113
	v_mov_b32_e32 v58, v113
	v_mov_b32_e32 v59, v113
	v_cvt_pk_bf16_f32 v73, v56, v57
	v_cndmask_b32_e32 v48, 0, v60, vcc
	v_mov_b32_dpp v49, v60 row_shl:4 row_mask:0xf bank_mask:0x1 bound_ctrl:1
	v_mov_b32_dpp v50, v60 row_shl:8 row_mask:0xf bank_mask:0x1 bound_ctrl:1
	v_mov_b32_dpp v51, v60 row_shl:12 row_mask:0xf bank_mask:0x1 bound_ctrl:1
	v_mov_b32_e32 v57, v113
	v_mov_b32_dpp v58, v63 row_shl:8 row_mask:0xf bank_mask:0x1 bound_ctrl:1
	v_mov_b32_dpp v59, v63 row_shl:12 row_mask:0xf bank_mask:0x1 bound_ctrl:1
	v_cvt_pk_bf16_f32 v75, v62, v68
	v_cndmask_b32_e32 v56, 0, v63, vcc
	v_mov_b32_dpp v57, v63 row_shl:4 row_mask:0xf bank_mask:0x1 bound_ctrl:1
	v_cvt_pk_bf16_f32 v68, v48, v49
	v_cvt_pk_bf16_f32 v69, v50, v51
	v_cvt_pk_bf16_f32 v71, v58, v59
	v_mov_b32_e32 v49, v113
	v_mov_b32_e32 v50, v113
	v_mov_b32_e32 v51, v113
	v_mov_b32_e32 v58, v113
	v_mov_b32_e32 v59, v113
	v_cvt_pk_bf16_f32 v70, v56, v57
	v_cndmask_b32_e32 v48, 0, v101, vcc
	v_mov_b32_dpp v49, v101 row_shl:4 row_mask:0xf bank_mask:0x1 bound_ctrl:1
	v_mov_b32_dpp v50, v101 row_shl:8 row_mask:0xf bank_mask:0x1 bound_ctrl:1
	v_mov_b32_dpp v51, v101 row_shl:12 row_mask:0xf bank_mask:0x1 bound_ctrl:1
	v_mov_b32_e32 v57, v113
	v_mov_b32_dpp v58, v102 row_shl:8 row_mask:0xf bank_mask:0x1 bound_ctrl:1
	v_mov_b32_dpp v59, v102 row_shl:12 row_mask:0xf bank_mask:0x1 bound_ctrl:1
	v_cndmask_b32_e32 v56, 0, v102, vcc
	v_mov_b32_dpp v57, v102 row_shl:4 row_mask:0xf bank_mask:0x1 bound_ctrl:1
	v_cvt_pk_bf16_f32 v60, v48, v49
	v_cvt_pk_bf16_f32 v61, v50, v51
	v_cvt_pk_bf16_f32 v63, v58, v59
	v_mov_b32_e32 v49, v113
	v_mov_b32_e32 v50, v113
	v_mov_b32_e32 v51, v113
	v_mov_b32_e32 v59, v113
	v_mov_b32_e32 v101, v113
	v_mov_b32_e32 v102, v113
	v_cndmask_b32_e32 v48, 0, v103, vcc
	v_mov_b32_dpp v49, v103 row_shl:4 row_mask:0xf bank_mask:0x1 bound_ctrl:1
	v_mov_b32_dpp v50, v103 row_shl:8 row_mask:0xf bank_mask:0x1 bound_ctrl:1
	v_mov_b32_dpp v51, v103 row_shl:12 row_mask:0xf bank_mask:0x1 bound_ctrl:1
	v_cndmask_b32_e32 v58, 0, v104, vcc
	v_mov_b32_dpp v59, v104 row_shl:4 row_mask:0xf bank_mask:0x1 bound_ctrl:1
	v_mov_b32_dpp v101, v104 row_shl:8 row_mask:0xf bank_mask:0x1 bound_ctrl:1
	v_mov_b32_dpp v102, v104 row_shl:12 row_mask:0xf bank_mask:0x1 bound_ctrl:1
	v_cvt_pk_bf16_f32 v62, v56, v57
	v_cvt_pk_bf16_f32 v56, v48, v49
	v_cvt_pk_bf16_f32 v57, v50, v51
	v_cvt_pk_bf16_f32 v58, v58, v59
	v_cvt_pk_bf16_f32 v59, v101, v102
	v_mov_b32_e32 v49, v113
	v_mov_b32_e32 v50, v113
	v_mov_b32_e32 v51, v113
	v_mov_b32_e32 v102, v113
	v_mov_b32_e32 v103, v113
	v_mov_b32_e32 v104, v113
	v_lshlrev_b32_e32 v100, 3, v120
	v_mov_b32_e32 v97, v96
	v_cndmask_b32_e32 v48, 0, v105, vcc
	v_mov_b32_dpp v49, v105 row_shl:4 row_mask:0xf bank_mask:0x1 bound_ctrl:1
	v_mov_b32_dpp v50, v105 row_shl:8 row_mask:0xf bank_mask:0x1 bound_ctrl:1
	v_mov_b32_dpp v51, v105 row_shl:12 row_mask:0xf bank_mask:0x1 bound_ctrl:1
	v_cndmask_b32_e32 v101, 0, v106, vcc
	v_mov_b32_dpp v102, v106 row_shl:4 row_mask:0xf bank_mask:0x1 bound_ctrl:1
	v_mov_b32_dpp v103, v106 row_shl:8 row_mask:0xf bank_mask:0x1 bound_ctrl:1
	v_mov_b32_dpp v104, v106 row_shl:12 row_mask:0xf bank_mask:0x1 bound_ctrl:1
	v_mul_u32_u24_e32 v98, 0xa0, v98
	v_and_b32_e32 v100, 24, v100
	v_mul_u32_u24_e32 v99, 0xa0, v122
	v_permlane32_swap_b32_e32 v96, v97
	v_cvt_pk_bf16_f32 v48, v48, v49
	v_cvt_pk_bf16_f32 v49, v50, v51
	v_cvt_pk_bf16_f32 v50, v101, v102
	v_cvt_pk_bf16_f32 v51, v103, v104
	v_add3_u32 v110, s47, v98, v100
	v_add_u32_e32 v111, v121, v99
	s_waitcnt vmcnt(15)
	ds_write_b128 v111, v[32:35] offset:1024
	s_waitcnt vmcnt(14)
	ds_write_b128 v111, v[36:39] offset:2304
	s_waitcnt vmcnt(13)
	ds_write_b128 v111, v[40:43] offset:3584
	s_waitcnt vmcnt(12)
	ds_write_b128 v111, v[44:47] offset:4864
	ds_read_b64_tr_b16 v[34:35], v110 offset:3584
	ds_read_b64_tr_b16 v[32:33], v110 offset:1024
	ds_read_b64_tr_b16 v[36:37], v110 offset:1056
	ds_read_b64_tr_b16 v[40:41], v110 offset:1088
	ds_read_b64_tr_b16 v[44:45], v110 offset:1120
	ds_read_b64_tr_b16 v[38:39], v110 offset:3616
	ds_read_b64_tr_b16 v[42:43], v110 offset:3648
	ds_read_b64_tr_b16 v[46:47], v110 offset:3680
	s_waitcnt lgkmcnt(6)
	v_mfma_f32_16x16x32_bf16 v[32:35], v[76:79], v[32:35], 0
	s_waitcnt lgkmcnt(0)
	global_load_dwordx4 v[98:101], v224, s[18:19]
	global_load_dwordx4 v[102:105], v225, s[18:19]
	global_load_dwordx4 v[106:109], v226, s[18:19]
	global_load_dwordx4 v[120:123], v227, s[18:19]
	v_mfma_f32_16x16x32_bf16 v[36:39], v[76:79], v[36:39], 0
	v_mfma_f32_16x16x32_bf16 v[40:43], v[76:79], v[40:43], 0
	v_mfma_f32_16x16x32_bf16 v[44:47], v[76:79], v[44:47], 0
	s_waitcnt vmcnt(15)
	ds_write_b128 v111, v[16:19] offset:1024
	s_waitcnt vmcnt(14)
	ds_write_b128 v111, v[20:23] offset:2304
	s_waitcnt vmcnt(13)
	ds_write_b128 v111, v[24:27] offset:3584
	s_waitcnt vmcnt(12)
	ds_write_b128 v111, v[28:31] offset:4864
	ds_read_b64_tr_b16 v[18:19], v110 offset:3584
	ds_read_b64_tr_b16 v[16:17], v110 offset:1024
	ds_read_b64_tr_b16 v[20:21], v110 offset:1056
	ds_read_b64_tr_b16 v[24:25], v110 offset:1088
	ds_read_b64_tr_b16 v[28:29], v110 offset:1120
	ds_read_b64_tr_b16 v[22:23], v110 offset:3616
	ds_read_b64_tr_b16 v[26:27], v110 offset:3648
	ds_read_b64_tr_b16 v[30:31], v110 offset:3680
	s_waitcnt lgkmcnt(6)
	v_mfma_f32_16x16x32_bf16 v[16:19], v[64:67], v[16:19], v[32:35]
	s_waitcnt lgkmcnt(1)
	v_mfma_f32_16x16x32_bf16 v[24:27], v[64:67], v[24:27], v[40:43]
	s_nop 0
	s_waitcnt lgkmcnt(0)
	v_mfma_f32_16x16x32_bf16 v[20:23], v[64:67], v[20:23], v[36:39]
	global_load_dwordx4 v[32:35], v228, s[18:19]
	s_nop 0
	global_load_dwordx4 v[36:39], v229, s[18:19]
	global_load_dwordx4 v[40:43], v230, s[18:19]
	global_load_dwordx4 v[76:79], v231, s[18:19]
	v_mfma_f32_16x16x32_bf16 v[28:31], v[64:67], v[28:31], v[44:47]
	s_waitcnt vmcnt(15)
	ds_write_b128 v111, v[0:3] offset:1024
	s_waitcnt vmcnt(14)
	ds_write_b128 v111, v[4:7] offset:2304
	s_waitcnt vmcnt(13)
	ds_write_b128 v111, v[8:11] offset:3584
	s_waitcnt vmcnt(12)
	ds_write_b128 v111, v[12:15] offset:4864
	ds_read_b64_tr_b16 v[2:3], v110 offset:3584
	ds_read_b64_tr_b16 v[0:1], v110 offset:1024
	ds_read_b64_tr_b16 v[4:5], v110 offset:1056
	ds_read_b64_tr_b16 v[8:9], v110 offset:1088
	ds_read_b64_tr_b16 v[12:13], v110 offset:1120
	ds_read_b64_tr_b16 v[6:7], v110 offset:3616
	ds_read_b64_tr_b16 v[10:11], v110 offset:3648
	ds_read_b64_tr_b16 v[14:15], v110 offset:3680
	s_waitcnt lgkmcnt(6)
	v_mfma_f32_16x16x32_bf16 v[0:3], v[52:55], v[0:3], v[16:19]
	s_waitcnt lgkmcnt(1)
	v_mfma_f32_16x16x32_bf16 v[8:11], v[52:55], v[8:11], v[24:27]
	s_nop 0
	s_waitcnt lgkmcnt(0)
	v_mfma_f32_16x16x32_bf16 v[4:7], v[52:55], v[4:7], v[20:23]
	global_load_dwordx4 v[16:19], v232, s[18:19]
	s_nop 0
	global_load_dwordx4 v[20:23], v233, s[18:19]
	global_load_dwordx4 v[24:27], v234, s[18:19]
	global_load_dwordx4 v[44:47], v235, s[18:19]
	v_mfma_f32_16x16x32_bf16 v[12:15], v[52:55], v[12:15], v[28:31]
	s_waitcnt vmcnt(15)
	ds_write_b128 v111, v[80:83] offset:1024
	s_waitcnt vmcnt(14)
	ds_write_b128 v111, v[84:87] offset:2304
	s_waitcnt vmcnt(13)
	ds_write_b128 v111, v[88:91] offset:3584
	s_waitcnt vmcnt(12)
	ds_write_b128 v111, v[92:95] offset:4864
	ds_read_b64_tr_b16 v[30:31], v110 offset:3584
	ds_read_b64_tr_b16 v[28:29], v110 offset:1024
	ds_read_b64_tr_b16 v[52:53], v110 offset:1056
	ds_read_b64_tr_b16 v[64:65], v110 offset:1088
	ds_read_b64_tr_b16 v[80:81], v110 offset:1120
	ds_read_b64_tr_b16 v[54:55], v110 offset:3616
	ds_read_b64_tr_b16 v[66:67], v110 offset:3648
	ds_read_b64_tr_b16 v[82:83], v110 offset:3680
	s_waitcnt lgkmcnt(6)
	v_mfma_f32_16x16x32_bf16 v[0:3], v[72:75], v[28:31], v[0:3]
	s_waitcnt lgkmcnt(0)
	v_mfma_f32_16x16x32_bf16 v[8:11], v[72:75], v[64:67], v[8:11]
	v_mfma_f32_16x16x32_bf16 v[4:7], v[72:75], v[52:55], v[4:7]
	global_load_dwordx4 v[28:31], v236, s[18:19]
	global_load_dwordx4 v[52:55], v237, s[18:19]
	global_load_dwordx4 v[64:67], v238, s[18:19]
	global_load_dwordx4 v[84:87], v239, s[18:19]
	v_mfma_f32_16x16x32_bf16 v[12:15], v[72:75], v[80:83], v[12:15]
	s_waitcnt vmcnt(15)
	ds_write_b128 v111, v[98:101] offset:1024
	s_waitcnt vmcnt(14)
	ds_write_b128 v111, v[102:105] offset:2304
	s_waitcnt vmcnt(13)
	ds_write_b128 v111, v[106:109] offset:3584
	s_waitcnt vmcnt(12)
	ds_write_b128 v111, v[120:123] offset:4864
	ds_read_b64_tr_b16 v[74:75], v110 offset:3584
	ds_read_b64_tr_b16 v[72:73], v110 offset:1024
	ds_read_b64_tr_b16 v[80:81], v110 offset:1056
	ds_read_b64_tr_b16 v[88:89], v110 offset:1088
	ds_read_b64_tr_b16 v[92:93], v110 offset:1120
	ds_read_b64_tr_b16 v[82:83], v110 offset:3616
	ds_read_b64_tr_b16 v[90:91], v110 offset:3648
	ds_read_b64_tr_b16 v[94:95], v110 offset:3680
	s_waitcnt lgkmcnt(6)
	v_mfma_f32_16x16x32_bf16 v[0:3], v[68:71], v[72:75], v[0:3]
	s_waitcnt lgkmcnt(2)
	v_mfma_f32_16x16x32_bf16 v[4:7], v[68:71], v[80:83], v[4:7]
	s_waitcnt lgkmcnt(1)
	v_mfma_f32_16x16x32_bf16 v[8:11], v[68:71], v[88:91], v[8:11]
	s_waitcnt lgkmcnt(0)
	v_mfma_f32_16x16x32_bf16 v[12:15], v[68:71], v[92:95], v[12:15]
	s_waitcnt vmcnt(11)
	ds_write_b128 v111, v[32:35] offset:1024
	s_waitcnt vmcnt(10)
	ds_write_b128 v111, v[36:39] offset:2304
	s_waitcnt vmcnt(9)
	ds_write_b128 v111, v[40:43] offset:3584
	s_waitcnt vmcnt(8)
	ds_write_b128 v111, v[76:79] offset:4864
	ds_read_b64_tr_b16 v[34:35], v110 offset:3584
	ds_read_b64_tr_b16 v[32:33], v110 offset:1024
	ds_read_b64_tr_b16 v[36:37], v110 offset:1056
	ds_read_b64_tr_b16 v[40:41], v110 offset:1088
	ds_read_b64_tr_b16 v[68:69], v110 offset:1120
	ds_read_b64_tr_b16 v[38:39], v110 offset:3616
	ds_read_b64_tr_b16 v[42:43], v110 offset:3648
	ds_read_b64_tr_b16 v[70:71], v110 offset:3680
	s_waitcnt lgkmcnt(6)
	v_mfma_f32_16x16x32_bf16 v[0:3], v[60:63], v[32:35], v[0:3]
	s_waitcnt lgkmcnt(2)
	v_mfma_f32_16x16x32_bf16 v[4:7], v[60:63], v[36:39], v[4:7]
	s_waitcnt lgkmcnt(1)
	v_mfma_f32_16x16x32_bf16 v[8:11], v[60:63], v[40:43], v[8:11]
	s_waitcnt lgkmcnt(0)
	v_mfma_f32_16x16x32_bf16 v[12:15], v[60:63], v[68:71], v[12:15]
	s_waitcnt vmcnt(7)
	ds_write_b128 v111, v[16:19] offset:1024
	s_waitcnt vmcnt(6)
	ds_write_b128 v111, v[20:23] offset:2304
	s_waitcnt vmcnt(5)
	ds_write_b128 v111, v[24:27] offset:3584
	s_waitcnt vmcnt(4)
	ds_write_b128 v111, v[44:47] offset:4864
	ds_read_b64_tr_b16 v[18:19], v110 offset:3584
	ds_read_b64_tr_b16 v[16:17], v110 offset:1024
	ds_read_b64_tr_b16 v[20:21], v110 offset:1056
	ds_read_b64_tr_b16 v[24:25], v110 offset:1088
	ds_read_b64_tr_b16 v[32:33], v110 offset:1120
	ds_read_b64_tr_b16 v[22:23], v110 offset:3616
	ds_read_b64_tr_b16 v[26:27], v110 offset:3648
	ds_read_b64_tr_b16 v[34:35], v110 offset:3680
	s_waitcnt lgkmcnt(6)
	v_mfma_f32_16x16x32_bf16 v[0:3], v[56:59], v[16:19], v[0:3]
	s_waitcnt lgkmcnt(2)
	v_mfma_f32_16x16x32_bf16 v[4:7], v[56:59], v[20:23], v[4:7]
	s_waitcnt lgkmcnt(1)
	v_mfma_f32_16x16x32_bf16 v[8:11], v[56:59], v[24:27], v[8:11]
	s_waitcnt lgkmcnt(0)
	v_mfma_f32_16x16x32_bf16 v[16:19], v[56:59], v[32:35], v[12:15]
	s_waitcnt vmcnt(3)
	ds_write_b128 v111, v[28:31] offset:1024
	s_waitcnt vmcnt(2)
	ds_write_b128 v111, v[52:55] offset:2304
	s_waitcnt vmcnt(1)
	ds_write_b128 v111, v[64:67] offset:3584
	s_waitcnt vmcnt(0)
	ds_write_b128 v111, v[84:87] offset:4864
	ds_read_b64_tr_b16 v[14:15], v110 offset:3584
	ds_read_b64_tr_b16 v[12:13], v110 offset:1024
	ds_read_b64_tr_b16 v[20:21], v110 offset:1056
	ds_read_b64_tr_b16 v[24:25], v110 offset:1088
	ds_read_b64_tr_b16 v[28:29], v110 offset:1120
	ds_read_b64_tr_b16 v[22:23], v110 offset:3616
	ds_read_b64_tr_b16 v[26:27], v110 offset:3648
	ds_read_b64_tr_b16 v[30:31], v110 offset:3680
	s_waitcnt lgkmcnt(6)
	v_mfma_f32_16x16x32_bf16 v[12:15], v[48:51], v[12:15], v[0:3]
	v_cmp_gt_u32_e32 vcc, 16, v117
	s_waitcnt lgkmcnt(1)
	v_mfma_f32_16x16x32_bf16 v[0:3], v[48:51], v[24:27], v[8:11]
	s_waitcnt lgkmcnt(0)
	v_mfma_f32_16x16x32_bf16 v[8:11], v[48:51], v[28:31], v[16:19]
	s_nop 2
	v_add_f32_e32 v19, v96, v97
	ds_bpermute_b32 v16, v114, v19
	ds_bpermute_b32 v17, v114, v19 offset:4
	ds_bpermute_b32 v18, v114, v19 offset:8
	ds_bpermute_b32 v19, v114, v19 offset:12
	v_mfma_f32_16x16x32_bf16 v[4:7], v[48:51], v[20:23], v[4:7]
	s_and_saveexec_b64 s[8:9], vcc
	s_cbranch_execz .LBB0_1251
	s_waitcnt lgkmcnt(0)
	v_div_scale_f32 v20, s[18:19], v19, v19, 1.0
	v_rcp_f32_e32 v21, v20
	v_div_scale_f32 v22, vcc, 1.0, v19, 1.0
	v_lshlrev_b32_e32 v112, 1, v116
	v_fma_f32 v23, -v20, v21, 1.0
	v_fmac_f32_e32 v21, v23, v21
	v_mul_f32_e32 v23, v22, v21
	v_fma_f32 v24, -v20, v23, v22
	v_fmac_f32_e32 v23, v24, v21
	v_fma_f32 v20, -v20, v23, v22
	v_div_scale_f32 v22, s[18:19], v18, v18, 1.0
	v_rcp_f32_e32 v24, v22
	v_div_fmas_f32 v20, v20, v21, v23
	v_div_fixup_f32 v19, v20, v19, 1.0
	v_fma_f32 v20, -v22, v24, 1.0
	v_fmac_f32_e32 v24, v20, v24
	v_div_scale_f32 v20, vcc, 1.0, v18, 1.0
	v_mul_f32_e32 v21, v20, v24
	v_fma_f32 v23, -v22, v21, v20
	v_fmac_f32_e32 v21, v23, v24
	v_fma_f32 v20, -v22, v21, v20
	v_div_scale_f32 v22, s[18:19], v17, v17, 1.0
	v_rcp_f32_e32 v23, v22
	v_div_fmas_f32 v20, v20, v24, v21
	v_div_fixup_f32 v18, v20, v18, 1.0
	v_fma_f32 v20, -v22, v23, 1.0
	v_fmac_f32_e32 v23, v20, v23
	v_div_scale_f32 v20, vcc, 1.0, v17, 1.0
	v_mul_f32_e32 v21, v20, v23
	v_fma_f32 v24, -v22, v21, v20
	v_fmac_f32_e32 v21, v24, v23
	v_fma_f32 v20, -v22, v21, v20
	v_div_scale_f32 v22, s[18:19], v16, v16, 1.0
	v_rcp_f32_e32 v24, v22
	v_div_fmas_f32 v20, v20, v23, v21
	v_div_fixup_f32 v20, v20, v17, 1.0
	v_fma_f32 v17, -v22, v24, 1.0
	v_fmac_f32_e32 v24, v17, v24
	v_div_scale_f32 v17, vcc, 1.0, v16, 1.0
	v_mul_f32_e32 v21, v17, v24
	v_fma_f32 v23, -v22, v21, v17
	v_fmac_f32_e32 v21, v23, v24
	v_fma_f32 v17, -v22, v21, v17
	v_div_fmas_f32 v17, v17, v24, v21
	v_div_fixup_f32 v21, v17, v16, 1.0
	v_mul_f32_e32 v12, v12, v21
	v_mul_f32_e32 v4, v4, v21
	v_mul_f32_e32 v0, v0, v21
	v_mul_f32_e32 v8, v8, v21
	v_mul_f32_e32 v13, v13, v20
	v_mul_f32_e32 v5, v5, v20
	v_mul_f32_e32 v1, v1, v20
	v_mul_f32_e32 v9, v9, v20
	v_mul_f32_e32 v14, v14, v18
	v_mul_f32_e32 v6, v6, v18
	v_mul_f32_e32 v2, v2, v18
	v_mul_f32_e32 v10, v10, v18
	v_mul_f32_e32 v15, v15, v19
	v_mul_f32_e32 v7, v7, v19
	v_mul_f32_e32 v3, v3, v19
	v_mul_f32_e32 v11, v11, v19
	v_lshl_add_u32 v25, v116, 1, s47
	v_cvt_pk_bf16_f32 v12, v12, v4
	v_cvt_pk_bf16_f32 v0, v0, v8
	v_cvt_pk_bf16_f32 v13, v13, v5
	v_cvt_pk_bf16_f32 v1, v1, v9
	v_cvt_pk_bf16_f32 v14, v14, v6
	v_cvt_pk_bf16_f32 v2, v2, v10
	v_cvt_pk_bf16_f32 v15, v15, v7
	v_cvt_pk_bf16_f32 v3, v3, v11
	ds_write_b16 v25, v12 offset:1024
	ds_write_b16_d16_hi v25, v12 offset:1056
	ds_write_b16 v25, v0 offset:1088
	ds_write_b16_d16_hi v25, v0 offset:1120
	ds_write_b16 v25, v13 offset:1152
	ds_write_b16_d16_hi v25, v13 offset:1184
	ds_write_b16 v25, v1 offset:1216
	ds_write_b16_d16_hi v25, v1 offset:1248
	ds_write_b16 v25, v14 offset:1280
	ds_write_b16_d16_hi v25, v14 offset:1312
	ds_write_b16 v25, v2 offset:1344
	ds_write_b16_d16_hi v25, v2 offset:1376
	ds_write_b16 v25, v15 offset:1408
	ds_write_b16_d16_hi v25, v15 offset:1440
	ds_write_b16 v25, v3 offset:1472
	ds_write_b16_d16_hi v25, v3 offset:1504
	s_mov_b32 exec_lo, -1
	s_mov_b32 exec_hi, 0
	v_lshl_add_u32 v26, v117, 4, s47
	v_lshlrev_b32_e32 v27, 4, v117
	s_add_u32 s18, s16, s14
	s_addc_u32 s19, s17, s15
	ds_read_b128 v[28:31], v26 offset:1024
	s_waitcnt lgkmcnt(0)
	global_store_dwordx4 v27, v[28:31], s[18:19]
	s_branch .LBB0_1251
